# split-update version with coalesced LDS waits (one s_waitcnt covers all loads issued >=24 instructions earlier)
# baseline (speedup 1.0000x reference)
.Lmy_ck_nz:
	s_mov_b32 s100, 0xe000
	s_cmp_eq_u32 s23, 0
	s_cselect_b32 s100, 0x1c000, s100
	s_mov_b32 s101, 0x12e00
	s_cselect_b32 s101, 0x22100, s101
	s_lshl_b32 s96, s23, 13
	s_add_i32 s97, s96, 0x18000
	s_add_i32 s96, s96, 0xa000
	v_add_u32_e32 v225, s100, v1
	v_add_u32_e32 v236, s100, v0
	v_add_u32_e32 v34, s100, v10
	v_add_u32_e32 v226, s100, v2
	v_add_u32_e32 v227, s100, v3
	v_add_u32_e32 v228, s100, v4
	v_add_u32_e32 v229, s100, v5
	v_add_u32_e32 v237, s100, v6
	v_add_u32_e32 v238, s100, v7
	v_add_u32_e32 v230, s96, v8
	v_add_u32_e32 v239, s96, v9
	v_add_u32_e32 v231, s97, v8
	v_add_u32_e32 v26, s101, v1
	v_add_u32_e32 v27, s101, v0
	v_add_u32_e32 v35, s101, v10
	v_add_u32_e32 v28, s101, v2
	v_add_u32_e32 v29, s101, v3
	v_add_u32_e32 v30, s101, v4
	v_add_u32_e32 v31, s101, v5
	v_add_u32_e32 v32, s101, v6
	v_add_u32_e32 v33, s101, v7
	ds_read_b64 v[80:81], v237
	ds_read_b64 v[82:83], v238
	ds_read_b32 v36, v239
	ds_read_b32 v37, v239 offset:256
	ds_read_b128 v[88:91], v225
	ds_read_b128 v[92:95], v225 offset:1024
	ds_read_b128 v[96:99], v225 offset:2048
	ds_read_b128 v[100:103], v225 offset:3072
	ds_read_b32 v104, v227 offset:4
	ds_read_b32 v105, v227 offset:76
	ds_read_b64 v[106:107], v227 offset:8
	ds_read_b64 v[108:109], v227 offset:40
	ds_read_b32 v126, v229 offset:4
	ds_read_b32 v127, v229 offset:76
	ds_read_b64 v[128:129], v229 offset:8
	ds_read_b64 v[130:131], v229 offset:40
	ds_read_b64 v[110:111], v228
	ds_read_b64 v[112:113], v228 offset:32
	ds_read_b64 v[114:115], v228 offset:64
	ds_read_b64 v[116:117], v228 offset:96
	ds_read_b64 v[118:119], v228 offset:8
	ds_read_b64 v[120:121], v228 offset:40
	ds_read_b64 v[122:123], v228 offset:72
	ds_read_b64 v[124:125], v228 offset:104
	s_waitcnt lgkmcnt(15)
	v_mfma_f32_16x16x4_f32 v[240:243], v80, v36, 0
	v_mfma_f32_16x16x4_f32 v[240:243], v81, v37, v[240:243]
	v_mfma_f32_16x16x4_f32 v[240:243], v88, v208, v[240:243]
	ds_read_b64 v[186:187], v34
	ds_read_b64 v[190:191], v34 offset:1024
	v_mfma_f32_16x16x4_f32 v[244:247], v89, v209, 0
	ds_read_b64 v[194:195], v34 offset:2048
	ds_read_b64 v[198:199], v34 offset:3072
	v_mfma_f32_16x16x4_f32 v[240:243], v90, v210, v[240:243]
	ds_read_b64 v[184:185], v236
	ds_read_b64 v[188:189], v236 offset:1024
	ds_read_b64 v[132:133], v237 offset:9984
	ds_read_b64 v[134:135], v238 offset:9984
	v_mfma_f32_16x16x4_f32 v[244:247], v91, v211, v[244:247]
	ds_read_b64 v[192:193], v236 offset:2048
	ds_read_b64 v[196:197], v236 offset:3072
	ds_read_b32 v38, v239 offset:2048
	ds_read_b32 v39, v239 offset:2304
	v_mfma_f32_16x16x4_f32 v[240:243], v92, v212, v[240:243]
	ds_read_b128 v[140:143], v225 offset:9984
	ds_read_b128 v[144:147], v225 offset:11008
	v_mfma_f32_16x16x4_f32 v[244:247], v93, v213, v[244:247]
	ds_read_b128 v[148:151], v225 offset:12032
	ds_read_b128 v[152:155], v225 offset:13056
	v_mfma_f32_16x16x4_f32 v[240:243], v94, v214, v[240:243]
	ds_read_b32 v156, v227 offset:9988
	ds_read_b32 v157, v227 offset:10060
	v_mfma_f32_16x16x4_f32 v[244:247], v95, v215, v[244:247]
	ds_read_b64 v[158:159], v227 offset:9992
	ds_read_b64 v[160:161], v227 offset:10024
	v_mfma_f32_16x16x4_f32 v[240:243], v96, v216, v[240:243]
	ds_read_b32 v178, v229 offset:9988
	ds_read_b32 v179, v229 offset:10060
	v_mfma_f32_16x16x4_f32 v[244:247], v97, v217, v[244:247]
	ds_read_b64 v[180:181], v229 offset:9992
	ds_read_b64 v[182:183], v229 offset:10024
	v_mfma_f32_16x16x4_f32 v[240:243], v98, v218, v[240:243]
	ds_read_b64 v[162:163], v228 offset:9984
	ds_read_b64 v[164:165], v228 offset:10016
	v_mfma_f32_16x16x4_f32 v[244:247], v99, v219, v[244:247]
	ds_read_b64 v[166:167], v228 offset:10048
	ds_read_b64 v[168:169], v228 offset:10080
	v_mfma_f32_16x16x4_f32 v[240:243], v100, v220, v[240:243]
	ds_read_b64 v[170:171], v228 offset:9992
	ds_read_b64 v[172:173], v228 offset:10024
	v_mfma_f32_16x16x4_f32 v[244:247], v101, v221, v[244:247]
	ds_read_b64 v[174:175], v228 offset:10056
	ds_read_b64 v[176:177], v228 offset:10088
	v_mfma_f32_16x16x4_f32 v[240:243], v102, v222, v[240:243]
	v_mfma_f32_16x16x4_f32 v[244:247], v103, v223, v[244:247]
	s_waitcnt lgkmcnt(14)
	v_mfma_f32_16x16x4_f32 v[208:211], v186, v36, v[208:211]
	s_nop 2
	v_pk_add_f32 v[240:241], v[240:241], v[244:245]
	v_pk_add_f32 v[242:243], v[242:243], v[246:247]
	v_fmac_f32_e32 v241, v104, v240
	v_mfma_f32_16x16x4_f32 v[212:215], v190, v36, v[212:215]
	v_pk_fma_f32 v[242:243], v[106:107], v[240:241], v[242:243] op_sel:[0,0,0] op_sel_hi:[1,0,1]
	v_pk_fma_f32 v[242:243], v[108:109], v[240:241], v[242:243] op_sel:[0,1,0] op_sel_hi:[1,1,1]
	v_fmac_f32_e32 v243, v105, v242
	v_mfma_f32_16x16x4_f32 v[216:219], v194, v36, v[216:219]
	ds_bpermute_b32 v204, v232, v240
	ds_bpermute_b32 v205, v232, v241
	ds_bpermute_b32 v206, v232, v242
	v_mfma_f32_16x16x4_f32 v[72:75], v132, v38, 0
	ds_bpermute_b32 v207, v232, v243
	ds_read_b128 v[88:91], v226
	ds_read_b128 v[92:95], v226 offset:64
	v_mfma_f32_16x16x4_f32 v[72:75], v133, v39, v[72:75]
	ds_read_b128 v[96:99], v226 offset:128
	ds_read_b128 v[100:103], v226 offset:192
	s_waitcnt lgkmcnt(6)
	v_pk_fma_f32 v[240:241], v[110:111], v[204:205], v[240:241] op_sel:[0,0,0] op_sel_hi:[1,0,1]
	v_mfma_f32_16x16x4_f32 v[220:223], v198, v36, v[220:223]
	v_pk_fma_f32 v[240:241], v[112:113], v[204:205], v[240:241] op_sel:[0,1,0] op_sel_hi:[1,1,1]
	s_waitcnt lgkmcnt(4)
	v_pk_fma_f32 v[240:241], v[114:115], v[206:207], v[240:241] op_sel:[0,0,0] op_sel_hi:[1,0,1]
	v_pk_fma_f32 v[240:241], v[116:117], v[206:207], v[240:241] op_sel:[0,1,0] op_sel_hi:[1,1,1]
	v_mfma_f32_16x16x4_f32 v[208:211], v187, v37, v[208:211]
	v_pk_fma_f32 v[242:243], v[118:119], v[204:205], v[242:243] op_sel:[0,0,0] op_sel_hi:[1,0,1]
	v_pk_fma_f32 v[242:243], v[120:121], v[204:205], v[242:243] op_sel:[0,1,0] op_sel_hi:[1,1,1]
	v_pk_fma_f32 v[242:243], v[122:123], v[206:207], v[242:243] op_sel:[0,0,0] op_sel_hi:[1,0,1]
	v_mfma_f32_16x16x4_f32 v[212:215], v191, v37, v[212:215]
	v_pk_fma_f32 v[242:243], v[124:125], v[206:207], v[242:243] op_sel:[0,1,0] op_sel_hi:[1,1,1]
	v_fmac_f32_e32 v241, v126, v240
	v_pk_fma_f32 v[242:243], v[128:129], v[240:241], v[242:243] op_sel:[0,0,0] op_sel_hi:[1,0,1]
	v_mfma_f32_16x16x4_f32 v[216:219], v195, v37, v[216:219]
	v_pk_fma_f32 v[242:243], v[130:131], v[240:241], v[242:243] op_sel:[0,1,0] op_sel_hi:[1,1,1]
	v_fmac_f32_e32 v243, v127, v242
	v_mov_b32_e32 v252, v240
	v_mfma_f32_16x16x4_f32 v[220:223], v199, v37, v[220:223]
	v_mov_b32_e32 v253, v241
	v_mov_b32_e32 v254, v242
	v_mov_b32_e32 v255, v243
	s_nop 0
	v_permlane32_swap_b32_e32 v252, v254
	v_permlane32_swap_b32_e32 v253, v255
	s_nop 0
	v_mfma_f32_16x16x4_f32 v[208:211], v184, v252, v[208:211]
	v_mfma_f32_16x16x4_f32 v[212:215], v188, v252, v[212:215]
	v_mfma_f32_16x16x4_f32 v[216:219], v192, v252, v[216:219]
	v_mfma_f32_16x16x4_f32 v[220:223], v196, v252, v[220:223]
	v_mfma_f32_16x16x4_f32 v[208:211], v185, v253, v[208:211]
	v_mfma_f32_16x16x4_f32 v[212:215], v189, v253, v[212:215]
	v_mfma_f32_16x16x4_f32 v[216:219], v193, v253, v[216:219]
	v_mfma_f32_16x16x4_f32 v[220:223], v197, v253, v[220:223]
	v_mfma_f32_16x16x4_f32 v[248:251], v82, v252, v[240:243]
	v_mfma_f32_16x16x4_f32 v[248:251], v83, v253, v[248:251]
	s_waitcnt lgkmcnt(0)
	v_pk_mul_f32 v[208:209], v[208:209], v[88:89]
	v_pk_mul_f32 v[210:211], v[210:211], v[90:91]
	s_nop 0
	v_mfma_f32_16x16x4_f32 v[72:75], v140, v208, v[72:75]
	v_pk_mul_f32 v[212:213], v[212:213], v[92:93]
	v_mfma_f32_16x16x4_f32 v[244:247], v141, v209, 0
	v_pk_mul_f32 v[214:215], v[214:215], v[94:95]
	v_mfma_f32_16x16x4_f32 v[72:75], v142, v210, v[72:75]
	v_pk_mul_f32 v[216:217], v[216:217], v[96:97]
	v_mfma_f32_16x16x4_f32 v[244:247], v143, v211, v[244:247]
	v_pk_mul_f32 v[218:219], v[218:219], v[98:99]
	v_mfma_f32_16x16x4_f32 v[72:75], v144, v212, v[72:75]
	v_pk_mul_f32 v[220:221], v[220:221], v[100:101]
	v_mfma_f32_16x16x4_f32 v[244:247], v145, v213, v[244:247]
	v_pk_mul_f32 v[222:223], v[222:223], v[102:103]
	v_mfma_f32_16x16x4_f32 v[72:75], v146, v214, v[72:75]
	s_mov_b64 exec, s[98:99]
	ds_write_b32 v231, v248
	ds_write_b32 v231, v249 offset:256
	ds_write_b32 v231, v250 offset:512
	ds_write_b32 v231, v251 offset:768
	s_mov_b64 exec, -1
	ds_read_b64 v[186:187], v34 offset:9984
	ds_read_b64 v[190:191], v34 offset:11008
	v_mfma_f32_16x16x4_f32 v[244:247], v147, v215, v[244:247]
	ds_read_b64 v[194:195], v34 offset:12032
	ds_read_b64 v[198:199], v34 offset:13056
	v_mfma_f32_16x16x4_f32 v[72:75], v148, v216, v[72:75]
	ds_read_b64 v[184:185], v236 offset:9984
	ds_read_b64 v[188:189], v236 offset:11008
	ds_read_b64 v[80:81], v32
	ds_read_b64 v[82:83], v33
	ds_read_b32 v36, v239 offset:4096
	v_mfma_f32_16x16x4_f32 v[244:247], v149, v217, v[244:247]
	ds_read_b64 v[192:193], v236 offset:12032
	ds_read_b64 v[196:197], v236 offset:13056
	ds_read_b32 v37, v239 offset:4352
	ds_read_b128 v[88:91], v26
	ds_read_b128 v[92:95], v26 offset:1024
	v_mfma_f32_16x16x4_f32 v[72:75], v150, v218, v[72:75]
	ds_read_b128 v[96:99], v26 offset:2048
	ds_read_b128 v[100:103], v26 offset:3072
	ds_read_b32 v104, v29 offset:4
	v_mfma_f32_16x16x4_f32 v[244:247], v151, v219, v[244:247]
	ds_read_b32 v105, v29 offset:76
	ds_read_b64 v[106:107], v29 offset:8
	ds_read_b64 v[108:109], v29 offset:40
	v_mfma_f32_16x16x4_f32 v[72:75], v152, v220, v[72:75]
	ds_read_b32 v126, v31 offset:4
	ds_read_b32 v127, v31 offset:76
	ds_read_b64 v[128:129], v31 offset:8
	v_mfma_f32_16x16x4_f32 v[244:247], v153, v221, v[244:247]
	ds_read_b64 v[130:131], v31 offset:40
	ds_read_b64 v[110:111], v30
	ds_read_b64 v[112:113], v30 offset:32
	v_mfma_f32_16x16x4_f32 v[72:75], v154, v222, v[72:75]
	ds_read_b64 v[114:115], v30 offset:64
	ds_read_b64 v[116:117], v30 offset:96
	ds_read_b64 v[118:119], v30 offset:8
	v_mfma_f32_16x16x4_f32 v[244:247], v155, v223, v[244:247]
	ds_read_b64 v[120:121], v30 offset:40
	ds_read_b64 v[122:123], v30 offset:72
	ds_read_b64 v[124:125], v30 offset:104
	s_waitcnt lgkmcnt(15)
	v_mfma_f32_16x16x4_f32 v[208:211], v186, v38, v[208:211]
	s_nop 5
	v_pk_add_f32 v[72:73], v[72:73], v[244:245]
	v_pk_add_f32 v[74:75], v[74:75], v[246:247]
	v_fmac_f32_e32 v73, v156, v72
	v_mfma_f32_16x16x4_f32 v[212:215], v190, v38, v[212:215]
	v_pk_fma_f32 v[74:75], v[158:159], v[72:73], v[74:75] op_sel:[0,0,0] op_sel_hi:[1,0,1]
	v_pk_fma_f32 v[74:75], v[160:161], v[72:73], v[74:75] op_sel:[0,1,0] op_sel_hi:[1,1,1]
	v_fmac_f32_e32 v75, v157, v74
	v_mfma_f32_16x16x4_f32 v[216:219], v194, v38, v[216:219]
	ds_bpermute_b32 v204, v232, v72
	ds_bpermute_b32 v205, v232, v73
	ds_bpermute_b32 v206, v232, v74
	v_mfma_f32_16x16x4_f32 v[240:243], v80, v36, 0
	ds_bpermute_b32 v207, v232, v75
	ds_read_b128 v[140:143], v226 offset:9984
	ds_read_b128 v[144:147], v226 offset:10048
	v_mfma_f32_16x16x4_f32 v[240:243], v81, v37, v[240:243]
	ds_read_b128 v[148:151], v226 offset:10112
	ds_read_b128 v[152:155], v226 offset:10176
	s_waitcnt lgkmcnt(6)
	v_pk_fma_f32 v[72:73], v[162:163], v[204:205], v[72:73] op_sel:[0,0,0] op_sel_hi:[1,0,1]
	v_mfma_f32_16x16x4_f32 v[220:223], v198, v38, v[220:223]
	v_pk_fma_f32 v[72:73], v[164:165], v[204:205], v[72:73] op_sel:[0,1,0] op_sel_hi:[1,1,1]
	s_waitcnt lgkmcnt(4)
	v_pk_fma_f32 v[72:73], v[166:167], v[206:207], v[72:73] op_sel:[0,0,0] op_sel_hi:[1,0,1]
	v_pk_fma_f32 v[72:73], v[168:169], v[206:207], v[72:73] op_sel:[0,1,0] op_sel_hi:[1,1,1]
	v_mfma_f32_16x16x4_f32 v[208:211], v187, v39, v[208:211]
	v_pk_fma_f32 v[74:75], v[170:171], v[204:205], v[74:75] op_sel:[0,0,0] op_sel_hi:[1,0,1]
	v_pk_fma_f32 v[74:75], v[172:173], v[204:205], v[74:75] op_sel:[0,1,0] op_sel_hi:[1,1,1]
	v_pk_fma_f32 v[74:75], v[174:175], v[206:207], v[74:75] op_sel:[0,0,0] op_sel_hi:[1,0,1]
	v_mfma_f32_16x16x4_f32 v[212:215], v191, v39, v[212:215]
	v_pk_fma_f32 v[74:75], v[176:177], v[206:207], v[74:75] op_sel:[0,1,0] op_sel_hi:[1,1,1]
	v_fmac_f32_e32 v73, v178, v72
	v_pk_fma_f32 v[74:75], v[180:181], v[72:73], v[74:75] op_sel:[0,0,0] op_sel_hi:[1,0,1]
	v_mfma_f32_16x16x4_f32 v[216:219], v195, v39, v[216:219]
	v_pk_fma_f32 v[74:75], v[182:183], v[72:73], v[74:75] op_sel:[0,1,0] op_sel_hi:[1,1,1]
	v_fmac_f32_e32 v75, v179, v74
	v_mov_b32_e32 v252, v72
	v_mfma_f32_16x16x4_f32 v[220:223], v199, v39, v[220:223]
	v_mov_b32_e32 v253, v73
	v_mov_b32_e32 v254, v74
	v_mov_b32_e32 v255, v75
	s_nop 0
	v_permlane32_swap_b32_e32 v252, v254
	v_permlane32_swap_b32_e32 v253, v255
	s_nop 0
	v_mfma_f32_16x16x4_f32 v[208:211], v184, v252, v[208:211]
	v_mfma_f32_16x16x4_f32 v[212:215], v188, v252, v[212:215]
	v_mfma_f32_16x16x4_f32 v[216:219], v192, v252, v[216:219]
	v_mfma_f32_16x16x4_f32 v[220:223], v196, v252, v[220:223]
	v_mfma_f32_16x16x4_f32 v[208:211], v185, v253, v[208:211]
	v_mfma_f32_16x16x4_f32 v[212:215], v189, v253, v[212:215]
	v_mfma_f32_16x16x4_f32 v[216:219], v193, v253, v[216:219]
	v_mfma_f32_16x16x4_f32 v[220:223], v197, v253, v[220:223]
	v_mfma_f32_16x16x4_f32 v[248:251], v134, v252, v[72:75]
	v_mfma_f32_16x16x4_f32 v[248:251], v135, v253, v[248:251]
	s_waitcnt lgkmcnt(0)
	v_pk_mul_f32 v[208:209], v[208:209], v[140:141]
	v_pk_mul_f32 v[210:211], v[210:211], v[142:143]
	s_nop 0
	v_mfma_f32_16x16x4_f32 v[240:243], v88, v208, v[240:243]
	v_pk_mul_f32 v[212:213], v[212:213], v[144:145]
	v_mfma_f32_16x16x4_f32 v[244:247], v89, v209, 0
	v_pk_mul_f32 v[214:215], v[214:215], v[146:147]
	v_mfma_f32_16x16x4_f32 v[240:243], v90, v210, v[240:243]
	v_pk_mul_f32 v[216:217], v[216:217], v[148:149]
	v_mfma_f32_16x16x4_f32 v[244:247], v91, v211, v[244:247]
	v_pk_mul_f32 v[218:219], v[218:219], v[150:151]
	v_mfma_f32_16x16x4_f32 v[240:243], v92, v212, v[240:243]
	v_pk_mul_f32 v[220:221], v[220:221], v[152:153]
	v_mfma_f32_16x16x4_f32 v[244:247], v93, v213, v[244:247]
	v_pk_mul_f32 v[222:223], v[222:223], v[154:155]
	v_mfma_f32_16x16x4_f32 v[240:243], v94, v214, v[240:243]
	s_mov_b64 exec, s[98:99]
	ds_write_b32 v231, v248 offset:2048
	ds_write_b32 v231, v249 offset:2304
	ds_write_b32 v231, v250 offset:2560
	ds_write_b32 v231, v251 offset:2816
	s_mov_b64 exec, -1
	ds_read_b64 v[186:187], v35
	ds_read_b64 v[190:191], v35 offset:1024
	v_mfma_f32_16x16x4_f32 v[244:247], v95, v215, v[244:247]
	ds_read_b64 v[194:195], v35 offset:2048
	ds_read_b64 v[198:199], v35 offset:3072
	v_mfma_f32_16x16x4_f32 v[240:243], v96, v216, v[240:243]
	ds_read_b64 v[184:185], v27
	ds_read_b64 v[188:189], v27 offset:1024
	ds_read_b64 v[132:133], v32 offset:9984
	ds_read_b64 v[134:135], v33 offset:9984
	ds_read_b32 v38, v239 offset:6144
	v_mfma_f32_16x16x4_f32 v[244:247], v97, v217, v[244:247]
	ds_read_b64 v[192:193], v27 offset:2048
	ds_read_b64 v[196:197], v27 offset:3072
	ds_read_b32 v39, v239 offset:6400
	ds_read_b128 v[140:143], v26 offset:9984
	ds_read_b128 v[144:147], v26 offset:11008
	v_mfma_f32_16x16x4_f32 v[240:243], v98, v218, v[240:243]
	ds_read_b128 v[148:151], v26 offset:12032
	ds_read_b128 v[152:155], v26 offset:13056
	ds_read_b32 v156, v29 offset:9988
	v_mfma_f32_16x16x4_f32 v[244:247], v99, v219, v[244:247]
	ds_read_b32 v157, v29 offset:10060
	ds_read_b64 v[158:159], v29 offset:9992
	ds_read_b64 v[160:161], v29 offset:10024
	v_mfma_f32_16x16x4_f32 v[240:243], v100, v220, v[240:243]
	ds_read_b32 v178, v31 offset:9988
	ds_read_b32 v179, v31 offset:10060
	ds_read_b64 v[180:181], v31 offset:9992
	v_mfma_f32_16x16x4_f32 v[244:247], v101, v221, v[244:247]
	ds_read_b64 v[182:183], v31 offset:10024
	ds_read_b64 v[162:163], v30 offset:9984
	ds_read_b64 v[164:165], v30 offset:10016
	v_mfma_f32_16x16x4_f32 v[240:243], v102, v222, v[240:243]
	ds_read_b64 v[166:167], v30 offset:10048
	ds_read_b64 v[168:169], v30 offset:10080
	ds_read_b64 v[170:171], v30 offset:9992
	v_mfma_f32_16x16x4_f32 v[244:247], v103, v223, v[244:247]
	ds_read_b64 v[172:173], v30 offset:10024
	ds_read_b64 v[174:175], v30 offset:10056
	ds_read_b64 v[176:177], v30 offset:10088
	s_waitcnt lgkmcnt(15)
	v_mfma_f32_16x16x4_f32 v[208:211], v186, v36, v[208:211]
	s_nop 5
	v_pk_add_f32 v[240:241], v[240:241], v[244:245]
	v_pk_add_f32 v[242:243], v[242:243], v[246:247]
	v_fmac_f32_e32 v241, v104, v240
	v_mfma_f32_16x16x4_f32 v[212:215], v190, v36, v[212:215]
	v_pk_fma_f32 v[242:243], v[106:107], v[240:241], v[242:243] op_sel:[0,0,0] op_sel_hi:[1,0,1]
	v_pk_fma_f32 v[242:243], v[108:109], v[240:241], v[242:243] op_sel:[0,1,0] op_sel_hi:[1,1,1]
	v_fmac_f32_e32 v243, v105, v242
	v_mfma_f32_16x16x4_f32 v[216:219], v194, v36, v[216:219]
	ds_bpermute_b32 v204, v232, v240
	ds_bpermute_b32 v205, v232, v241
	ds_bpermute_b32 v206, v232, v242
	v_mfma_f32_16x16x4_f32 v[72:75], v132, v38, 0
	ds_bpermute_b32 v207, v232, v243
	ds_read_b128 v[88:91], v28
	ds_read_b128 v[92:95], v28 offset:64
	v_mfma_f32_16x16x4_f32 v[72:75], v133, v39, v[72:75]
	ds_read_b128 v[96:99], v28 offset:128
	ds_read_b128 v[100:103], v28 offset:192
	s_waitcnt lgkmcnt(6)
	v_pk_fma_f32 v[240:241], v[110:111], v[204:205], v[240:241] op_sel:[0,0,0] op_sel_hi:[1,0,1]
	v_mfma_f32_16x16x4_f32 v[220:223], v198, v36, v[220:223]
	v_pk_fma_f32 v[240:241], v[112:113], v[204:205], v[240:241] op_sel:[0,1,0] op_sel_hi:[1,1,1]
	s_waitcnt lgkmcnt(4)
	v_pk_fma_f32 v[240:241], v[114:115], v[206:207], v[240:241] op_sel:[0,0,0] op_sel_hi:[1,0,1]
	v_pk_fma_f32 v[240:241], v[116:117], v[206:207], v[240:241] op_sel:[0,1,0] op_sel_hi:[1,1,1]
	v_mfma_f32_16x16x4_f32 v[208:211], v187, v37, v[208:211]
	v_pk_fma_f32 v[242:243], v[118:119], v[204:205], v[242:243] op_sel:[0,0,0] op_sel_hi:[1,0,1]
	v_pk_fma_f32 v[242:243], v[120:121], v[204:205], v[242:243] op_sel:[0,1,0] op_sel_hi:[1,1,1]
	v_pk_fma_f32 v[242:243], v[122:123], v[206:207], v[242:243] op_sel:[0,0,0] op_sel_hi:[1,0,1]
	v_mfma_f32_16x16x4_f32 v[212:215], v191, v37, v[212:215]
	v_pk_fma_f32 v[242:243], v[124:125], v[206:207], v[242:243] op_sel:[0,1,0] op_sel_hi:[1,1,1]
	v_fmac_f32_e32 v241, v126, v240
	v_pk_fma_f32 v[242:243], v[128:129], v[240:241], v[242:243] op_sel:[0,0,0] op_sel_hi:[1,0,1]
	v_mfma_f32_16x16x4_f32 v[216:219], v195, v37, v[216:219]
	v_pk_fma_f32 v[242:243], v[130:131], v[240:241], v[242:243] op_sel:[0,1,0] op_sel_hi:[1,1,1]
	v_fmac_f32_e32 v243, v127, v242
	v_mov_b32_e32 v252, v240
	v_mfma_f32_16x16x4_f32 v[220:223], v199, v37, v[220:223]
	v_mov_b32_e32 v253, v241
	v_mov_b32_e32 v254, v242
	v_mov_b32_e32 v255, v243
	s_nop 0
	v_permlane32_swap_b32_e32 v252, v254
	v_permlane32_swap_b32_e32 v253, v255
	s_nop 0
	v_mfma_f32_16x16x4_f32 v[208:211], v184, v252, v[208:211]
	v_mfma_f32_16x16x4_f32 v[212:215], v188, v252, v[212:215]
	v_mfma_f32_16x16x4_f32 v[216:219], v192, v252, v[216:219]
	v_mfma_f32_16x16x4_f32 v[220:223], v196, v252, v[220:223]
	v_mfma_f32_16x16x4_f32 v[208:211], v185, v253, v[208:211]
	v_mfma_f32_16x16x4_f32 v[212:215], v189, v253, v[212:215]
	v_mfma_f32_16x16x4_f32 v[216:219], v193, v253, v[216:219]
	v_mfma_f32_16x16x4_f32 v[220:223], v197, v253, v[220:223]
	v_mfma_f32_16x16x4_f32 v[248:251], v82, v252, v[240:243]
	v_mfma_f32_16x16x4_f32 v[248:251], v83, v253, v[248:251]
	s_waitcnt lgkmcnt(0)
	v_pk_mul_f32 v[208:209], v[208:209], v[88:89]
	v_pk_mul_f32 v[210:211], v[210:211], v[90:91]
	s_nop 0
	v_mfma_f32_16x16x4_f32 v[72:75], v140, v208, v[72:75]
	v_pk_mul_f32 v[212:213], v[212:213], v[92:93]
	v_mfma_f32_16x16x4_f32 v[244:247], v141, v209, 0
	v_pk_mul_f32 v[214:215], v[214:215], v[94:95]
	v_mfma_f32_16x16x4_f32 v[72:75], v142, v210, v[72:75]
	v_pk_mul_f32 v[216:217], v[216:217], v[96:97]
	v_mfma_f32_16x16x4_f32 v[244:247], v143, v211, v[244:247]
	v_pk_mul_f32 v[218:219], v[218:219], v[98:99]
	v_mfma_f32_16x16x4_f32 v[72:75], v144, v212, v[72:75]
	v_pk_mul_f32 v[220:221], v[220:221], v[100:101]
	v_mfma_f32_16x16x4_f32 v[244:247], v145, v213, v[244:247]
	v_pk_mul_f32 v[222:223], v[222:223], v[102:103]
	v_mfma_f32_16x16x4_f32 v[72:75], v146, v214, v[72:75]
	s_mov_b64 exec, s[98:99]
	ds_write_b32 v231, v248 offset:4096
	ds_write_b32 v231, v249 offset:4352
	ds_write_b32 v231, v250 offset:4608
	ds_write_b32 v231, v251 offset:4864
	s_mov_b64 exec, -1
	ds_read_b64 v[186:187], v35 offset:9984
	ds_read_b64 v[190:191], v35 offset:11008
	v_mfma_f32_16x16x4_f32 v[244:247], v147, v215, v[244:247]
	ds_read_b64 v[194:195], v35 offset:12032
	ds_read_b64 v[198:199], v35 offset:13056
	v_mfma_f32_16x16x4_f32 v[72:75], v148, v216, v[72:75]
	ds_read_b64 v[184:185], v27 offset:9984
	ds_read_b64 v[188:189], v27 offset:11008
	v_mfma_f32_16x16x4_f32 v[244:247], v149, v217, v[244:247]
	ds_read_b64 v[192:193], v27 offset:12032
	ds_read_b64 v[196:197], v27 offset:13056
	v_mfma_f32_16x16x4_f32 v[72:75], v150, v218, v[72:75]
	v_mfma_f32_16x16x4_f32 v[244:247], v151, v219, v[244:247]
	v_mfma_f32_16x16x4_f32 v[72:75], v152, v220, v[72:75]
	v_mfma_f32_16x16x4_f32 v[244:247], v153, v221, v[244:247]
	v_mfma_f32_16x16x4_f32 v[72:75], v154, v222, v[72:75]
	v_mfma_f32_16x16x4_f32 v[244:247], v155, v223, v[244:247]
	s_waitcnt lgkmcnt(7)
	v_mfma_f32_16x16x4_f32 v[208:211], v186, v38, v[208:211]
	s_nop 2
	v_pk_add_f32 v[72:73], v[72:73], v[244:245]
	v_pk_add_f32 v[74:75], v[74:75], v[246:247]
	v_fmac_f32_e32 v73, v156, v72
	s_waitcnt lgkmcnt(6)
	v_mfma_f32_16x16x4_f32 v[212:215], v190, v38, v[212:215]
	v_pk_fma_f32 v[74:75], v[158:159], v[72:73], v[74:75] op_sel:[0,0,0] op_sel_hi:[1,0,1]
	v_pk_fma_f32 v[74:75], v[160:161], v[72:73], v[74:75] op_sel:[0,1,0] op_sel_hi:[1,1,1]
	v_fmac_f32_e32 v75, v157, v74
	s_waitcnt lgkmcnt(4)
	v_mfma_f32_16x16x4_f32 v[216:219], v194, v38, v[216:219]
	ds_bpermute_b32 v204, v232, v72
	ds_bpermute_b32 v205, v232, v73
	ds_bpermute_b32 v206, v232, v74
	v_mfma_f32_16x16x4_f32 v[220:223], v198, v38, v[220:223]
	ds_bpermute_b32 v207, v232, v75
	ds_read_b128 v[140:143], v28 offset:9984
	ds_read_b128 v[144:147], v28 offset:10048
	v_mfma_f32_16x16x4_f32 v[208:211], v187, v39, v[208:211]
	ds_read_b128 v[148:151], v28 offset:10112
	ds_read_b128 v[152:155], v28 offset:10176
	s_waitcnt lgkmcnt(6)
	v_pk_fma_f32 v[72:73], v[162:163], v[204:205], v[72:73] op_sel:[0,0,0] op_sel_hi:[1,0,1]
	v_mfma_f32_16x16x4_f32 v[212:215], v191, v39, v[212:215]
	v_pk_fma_f32 v[72:73], v[164:165], v[204:205], v[72:73] op_sel:[0,1,0] op_sel_hi:[1,1,1]
	s_waitcnt lgkmcnt(4)
	v_pk_fma_f32 v[72:73], v[166:167], v[206:207], v[72:73] op_sel:[0,0,0] op_sel_hi:[1,0,1]
	v_pk_fma_f32 v[72:73], v[168:169], v[206:207], v[72:73] op_sel:[0,1,0] op_sel_hi:[1,1,1]
	v_mfma_f32_16x16x4_f32 v[216:219], v195, v39, v[216:219]
	v_pk_fma_f32 v[74:75], v[170:171], v[204:205], v[74:75] op_sel:[0,0,0] op_sel_hi:[1,0,1]
	v_pk_fma_f32 v[74:75], v[172:173], v[204:205], v[74:75] op_sel:[0,1,0] op_sel_hi:[1,1,1]
	v_pk_fma_f32 v[74:75], v[174:175], v[206:207], v[74:75] op_sel:[0,0,0] op_sel_hi:[1,0,1]
	v_mfma_f32_16x16x4_f32 v[220:223], v199, v39, v[220:223]
	v_pk_fma_f32 v[74:75], v[176:177], v[206:207], v[74:75] op_sel:[0,1,0] op_sel_hi:[1,1,1]
	v_fmac_f32_e32 v73, v178, v72
	v_pk_fma_f32 v[74:75], v[180:181], v[72:73], v[74:75] op_sel:[0,0,0] op_sel_hi:[1,0,1]
	v_pk_fma_f32 v[74:75], v[182:183], v[72:73], v[74:75] op_sel:[0,1,0] op_sel_hi:[1,1,1]
	v_fmac_f32_e32 v75, v179, v74
	v_mov_b32_e32 v252, v72
	v_mov_b32_e32 v253, v73
	v_mov_b32_e32 v254, v74
	v_mov_b32_e32 v255, v75
	s_nop 0
	v_permlane32_swap_b32_e32 v252, v254
	v_permlane32_swap_b32_e32 v253, v255
	s_nop 0
	v_mfma_f32_16x16x4_f32 v[208:211], v184, v252, v[208:211]
	v_mfma_f32_16x16x4_f32 v[212:215], v188, v252, v[212:215]
	v_mfma_f32_16x16x4_f32 v[216:219], v192, v252, v[216:219]
	v_mfma_f32_16x16x4_f32 v[220:223], v196, v252, v[220:223]
	v_mfma_f32_16x16x4_f32 v[208:211], v185, v253, v[208:211]
	v_mfma_f32_16x16x4_f32 v[212:215], v189, v253, v[212:215]
	v_mfma_f32_16x16x4_f32 v[216:219], v193, v253, v[216:219]
	v_mfma_f32_16x16x4_f32 v[220:223], v197, v253, v[220:223]
	v_mfma_f32_16x16x4_f32 v[248:251], v134, v252, v[72:75]
	v_mfma_f32_16x16x4_f32 v[248:251], v135, v253, v[248:251]
	s_waitcnt lgkmcnt(0)
	v_pk_mul_f32 v[208:209], v[208:209], v[140:141]
	v_pk_mul_f32 v[210:211], v[210:211], v[142:143]
	v_pk_mul_f32 v[212:213], v[212:213], v[144:145]
	v_pk_mul_f32 v[214:215], v[214:215], v[146:147]
	v_pk_mul_f32 v[216:217], v[216:217], v[148:149]
	v_pk_mul_f32 v[218:219], v[218:219], v[150:151]
	v_pk_mul_f32 v[220:221], v[220:221], v[152:153]
	v_pk_mul_f32 v[222:223], v[222:223], v[154:155]
	s_mov_b64 exec, s[98:99]
	s_nop 0
	ds_write_b32 v231, v248 offset:6144
	ds_write_b32 v231, v249 offset:6400
	ds_write_b32 v231, v250 offset:6656
	ds_write_b32 v231, v251 offset:6912
	s_mov_b64 exec, -1
	s_branch .LBB0_655

.Lmy_ck_drE_h:
	s_waitcnt lgkmcnt(0)
	s_bfe_u32 s96, s62, 0x20006
	s_and_b32 s97, s96, 1
	s_mul_i32 s97, s97, 0x2700
	s_mov_b32 s101, 0x1c000
	s_mov_b32 s100, 0x6100
	s_bitcmp0_b32 s65, 0
	s_cselect_b32 s101, 0xe000, s101
	s_cselect_b32 s100, 0x4e00, s100
	s_cmp_gt_u32 s96, 1
	s_cselect_b32 s100, s100, 0
	s_add_i32 s97, s97, s101
	s_add_i32 s97, s97, s100
	s_mov_b32 s96, s97
	v_and_b32_e32 v72, 3, v233
	v_lshrrev_b32_e32 v73, 2, v233
	v_lshlrev_b32_e32 v72, 2, v72
	v_lshl_add_u32 v72, v73, 8, v72
	v_lshl_add_u32 v72, v234, 6, v72
	s_add_i32 s97, s96, 0x1000
	v_add_u32_e32 v78, s97, v72
	v_xor_b32_e32 v79, v224, v234
	v_lshl_add_u32 v79, v79, 4, s96
	ds_read_b128 v[96:99], v79
	ds_read_b128 v[100:103], v79 offset:1024
	ds_read_b128 v[104:107], v79 offset:2048
	ds_read_b128 v[108:111], v79 offset:3072
	ds_read_b32 v80, v78
	ds_read_b32 v81, v78 offset:16
	ds_read_b32 v82, v78 offset:32
	ds_read_b32 v83, v78 offset:48
	ds_read_b32 v84, v78 offset:1024
	ds_read_b32 v85, v78 offset:1040
	ds_read_b32 v86, v78 offset:1056
	ds_read_b32 v87, v78 offset:1072
	ds_read_b32 v88, v78 offset:2048
	ds_read_b32 v89, v78 offset:2064
	ds_read_b32 v90, v78 offset:2080
	ds_read_b32 v91, v78 offset:2096
	ds_read_b32 v92, v78 offset:3072
	ds_read_b32 v93, v78 offset:3088
	ds_read_b32 v94, v78 offset:3104
	ds_read_b32 v95, v78 offset:3120
	v_lshl_add_u32 v74, v224, 2, s96
	ds_write_b32 v74, v235 offset:9728
	v_add_u32_e32 v75, -1, v233
	v_mov_b32_e32 v76, -1
	v_cndmask_b32_e64 v75, v76, v75, s[98:99]
	v_cmp_lt_u32_e64 s[100:101], 7, v233
	v_add_u32_e32 v76, -8, v233
	v_and_b32_e32 v77, 1, v234
	v_cndmask_b32_e64 v75, v75, v76, s[100:101]
	v_lshlrev_b32_e32 v77, 2, v77
	v_sub_u32_e32 v76, v75, v77
	v_lshlrev_b32_e32 v77, 2, v234
	v_sub_u32_e32 v77, v233, v77
	v_add_u32_e32 v77, -1, v77
	s_waitcnt lgkmcnt(10)
	v_mfma_f32_16x16x4_f32 v[244:247], v80, v96, 0
	v_mfma_f32_16x16x4_f32 v[240:243], v81, v97, 0
	v_mfma_f32_16x16x4_f32 v[244:247], v82, v98, v[244:247]
	v_mfma_f32_16x16x4_f32 v[240:243], v83, v99, v[240:243]
	v_mfma_f32_16x16x4_f32 v[244:247], v84, v100, v[244:247]
	v_mfma_f32_16x16x4_f32 v[240:243], v85, v101, v[240:243]
	v_mfma_f32_16x16x4_f32 v[244:247], v86, v102, v[244:247]
	s_waitcnt lgkmcnt(2)
	v_mfma_f32_16x16x4_f32 v[240:243], v87, v103, v[240:243]
	v_mfma_f32_16x16x4_f32 v[244:247], v88, v104, v[244:247]
	v_mfma_f32_16x16x4_f32 v[240:243], v89, v105, v[240:243]
	v_mfma_f32_16x16x4_f32 v[244:247], v90, v106, v[244:247]
	v_mfma_f32_16x16x4_f32 v[240:243], v91, v107, v[240:243]
	v_mfma_f32_16x16x4_f32 v[244:247], v92, v108, v[244:247]
	v_mfma_f32_16x16x4_f32 v[240:243], v93, v109, v[240:243]
	v_mfma_f32_16x16x4_f32 v[244:247], v94, v110, v[244:247]
	s_waitcnt lgkmcnt(1)
	v_mfma_f32_16x16x4_f32 v[240:243], v95, v111, v[240:243]
	s_nop 9
	v_add_f32_e32 v244, v244, v240
	v_add_f32_e32 v245, v245, v241
	v_add_f32_e32 v246, v246, v242
	v_add_f32_e32 v247, v247, v243
	v_cmp_le_i32_e64 s[96:97], 0, v76
	v_cmp_le_i32_e64 s[100:101], 1, v76
	s_nop 0
	v_cndmask_b32_e64 v128, 0, v244, s[96:97]
	v_cndmask_b32_e64 v129, 0, v245, s[100:101]
	v_cmp_le_i32_e64 s[96:97], 2, v76
	v_cmp_le_i32_e64 s[100:101], 3, v76
	s_nop 0
	v_cndmask_b32_e64 v130, 0, v246, s[96:97]
	v_cndmask_b32_e64 v131, 0, v247, s[100:101]
	s_bfe_u32 s96, s62, 0x20006
	s_and_b32 s97, s96, 1
	s_mul_i32 s97, s97, 0x2700
	s_mov_b32 s101, 0x1c000
	s_mov_b32 s100, 0x6100
	s_bitcmp0_b32 s65, 0
	s_cselect_b32 s101, 0xe000, s101
	s_cselect_b32 s100, 0x4e00, s100
	s_cmp_gt_u32 s96, 1
	s_cselect_b32 s100, s100, 0
	s_add_i32 s97, s97, s101
	s_add_i32 s97, s97, s100
	v_xor_b32_e32 v74, v224, v234
	v_lshl_add_u32 v74, v74, 4, s97
	ds_write_b128 v74, v[128:131] offset:8448
	v_lshlrev_b32_e32 v75, 7, v234
	v_lshl_add_u32 v75, v233, 2, v75
	v_add_u32_e32 v75, s97, v75
	v_cmp_le_i32_e64 s[96:97], 0, v77
	v_cmp_le_i32_e64 s[100:101], 1, v77
	s_nop 0
	v_cndmask_b32_e64 v132, 0, v244, s[96:97]
	v_cndmask_b32_e64 v133, 0, v245, s[100:101]
	v_cmp_le_i32_e64 s[96:97], 2, v77
	v_cmp_le_i32_e64 s[100:101], 3, v77
	s_nop 0
	v_cndmask_b32_e64 v134, 0, v246, s[96:97]
	v_cndmask_b32_e64 v135, 0, v247, s[100:101]
	s_mov_b64 exec, 0x00ff00ff
	ds_write_b32 v75, v132 offset:9472
	ds_write_b32 v75, v133 offset:9504
	ds_write_b32 v75, v134 offset:9536
	ds_write_b32 v75, v135 offset:9568
	s_mov_b64 exec, -1
	s_setprio 0
	s_branch .LBB0_655
	s_nop 0
	s_nop 0
	s_nop 0
	s_nop 0
	s_nop 0
	s_nop 0
	s_nop 0
	s_nop 0
	s_nop 0
	s_nop 0
	s_nop 0
	s_nop 0
	s_nop 0
	s_nop 0
	s_nop 0
	s_nop 0
	s_nop 0
	s_nop 0
	s_nop 0
	s_nop 0
	s_nop 0
	s_nop 0
	s_nop 0
	s_nop 0
	s_nop 0
	s_nop 0
	s_nop 0
	s_nop 0
	s_nop 0
	s_nop 0
	s_nop 0
	s_nop 0
	s_nop 0
	s_nop 0
	s_nop 0
	s_nop 0
	s_nop 0
	s_nop 0
	s_nop 0
	s_nop 0
	s_nop 0
	s_nop 0
	s_nop 0
	s_nop 0
	s_nop 0
	s_nop 0
	s_nop 0
	s_nop 0
	s_nop 0
	s_nop 0
	s_nop 0
	s_nop 0
	s_nop 0
	s_nop 0
	s_nop 0
	s_nop 0
	s_nop 0
